# MODE0 attention tile: redundant scalar flag ops removed (SCC reused for near/far and first-tile flags)
# baseline (speedup 1.0000x reference)
; #define LAS __attribute__((address_space(3)))
; template <int MODE>
; __device__ __forceinline__ void attn_unit(LAS unsigned char* lds, const Ptrs& P, int nq, int nt_block, int qpos0, bool sample, int h,
;                                           const float* relb  , const float* lamp, const float* subg, bf16_t* Obase  , int wv) {
;     ...
;                 const int k0 = t * 64;
;                 const bool farT = (k0 + 63 - qmin <= -91);
;                 const int ib = k0 - qposl + 192 + 4 * hi;
;                 bf16x8 pa[4], pb[4];
;                 bf16x8 kf[4], kg2[4];
; #pragma unroll
;                 for (int ks = 0; ks < 2; ++ks) { kf[2 * ks] = *(const LAS bf16x8*)(kb + ks * 2048); kf[2 * ks + 1] = *(const LAS bf16x8*)(kb + ks * 2048 + 512); }
;                 {
;                     f32x16 p0, p1;
;                     if (farT) {
;                         p0 = __builtin_amdgcn_mfma_f32_32x32x16_bf16(kf[0], qf[0], ng1, 0, 0, 0);
;                         p1 = __builtin_amdgcn_mfma_f32_32x32x16_bf16(kf[1], qf[0], ng1, 0, 0, 0);
;                     } else {
;                         const float nb = ng1[0] - cbias;
; #pragma unroll
;                         for (int r = 0; r < 16; ++r) { const int idx = ib + (r & 3) + 8 * (r >> 2); p0[r] = bt[idx] + nb; p1[r] = bt[idx + 32] + nb; }
;                         p0 = __builtin_amdgcn_mfma_f32_32x32x16_bf16(kf[0], qf[0], p0, 0, 0, 0);
;                         p1 = __builtin_amdgcn_mfma_f32_32x32x16_bf16(kf[1], qf[0], p1, 0, 0, 0);
;                     }
.LBB0_1226:
	s_or_b32 s28, s24, s41
	s_cmp_ge_i32 s15, s28
	s_cselect_b64 s[2:3], -1, 0
	s_and_b64 s[2:3], s[38:39], s[2:3]
	s_andn2_b64 vcc, exec, s[2:3]
	s_cbranch_vccnz .LBB0_1225
	s_mul_i32 s2, s24, 0x5000
	s_add_i32 s42, s37, s2
	v_add_u32_e32 v4, s42, v244
	ds_read_b128 v[76:79], v4
	ds_read_b128 v[80:83], v4 offset:512
	ds_read_b128 v[72:75], v4 offset:2048
	ds_read_b128 v[150:153], v4 offset:2560
	s_lshl_b32 s2, s28, 6
	s_sub_i32 s3, s2, s8
	s_cmpk_gt_i32 s3, 0xff66
	s_cselect_b64 s[26:27], -1, 0
	s_mov_b64 s[2:3], -1
	s_cbranch_scc0 .Lm0p_far1
	s_lshl_b32 s2, s28, 6
	v_add_u32_e32 v84, s2, v232
	v_lshl_add_u32 v84, v84, 2, 0
	v_add_u32_e32 v85, 0x14000, v84
	ds_read2_b32 v[118:119], v85 offset1:1
	ds_read2_b32 v[120:121], v85 offset0:2 offset1:3
	ds_read2_b32 v[122:123], v85 offset0:8 offset1:9
	ds_read2_b32 v[124:125], v85 offset0:10 offset1:11
	ds_read2_b32 v[126:127], v85 offset0:16 offset1:17
	ds_read2_b32 v[128:129], v85 offset0:18 offset1:19
	ds_read2_b32 v[130:131], v85 offset0:24 offset1:25
	ds_read2_b32 v[132:133], v85 offset0:26 offset1:27
	ds_read2_b32 v[154:155], v85 offset0:32 offset1:33
	ds_read2_b32 v[136:137], v85 offset0:34 offset1:35
	ds_read2_b32 v[138:139], v85 offset0:40 offset1:41
	ds_read2_b32 v[140:141], v85 offset0:42 offset1:43
	ds_read2_b32 v[142:143], v85 offset0:48 offset1:49
	ds_read2_b32 v[144:145], v85 offset0:50 offset1:51
	ds_read2_b32 v[146:147], v85 offset0:56 offset1:57
	ds_read2_b32 v[148:149], v85 offset0:58 offset1:59
	v_sub_f32_e32 v134, v102, v70
	s_waitcnt lgkmcnt(8)
	v_pk_add_f32 v[132:133], v[134:135], v[132:133] op_sel_hi:[0,1]
	v_pk_add_f32 v[130:131], v[134:135], v[130:131] op_sel_hi:[0,1]
	v_pk_add_f32 v[128:129], v[134:135], v[128:129] op_sel_hi:[0,1]
	v_pk_add_f32 v[126:127], v[134:135], v[126:127] op_sel_hi:[0,1]
	v_pk_add_f32 v[124:125], v[134:135], v[124:125] op_sel_hi:[0,1]
	v_pk_add_f32 v[122:123], v[134:135], v[122:123] op_sel_hi:[0,1]
	v_pk_add_f32 v[120:121], v[134:135], v[120:121] op_sel_hi:[0,1]
	v_pk_add_f32 v[118:119], v[134:135], v[118:119] op_sel_hi:[0,1]
	s_waitcnt lgkmcnt(0)
	v_pk_add_f32 v[148:149], v[134:135], v[148:149] op_sel_hi:[0,1]
	v_pk_add_f32 v[146:147], v[134:135], v[146:147] op_sel_hi:[0,1]
	v_pk_add_f32 v[144:145], v[134:135], v[144:145] op_sel_hi:[0,1]
	v_pk_add_f32 v[142:143], v[134:135], v[142:143] op_sel_hi:[0,1]
	v_pk_add_f32 v[140:141], v[134:135], v[140:141] op_sel_hi:[0,1]
	v_pk_add_f32 v[138:139], v[134:135], v[138:139] op_sel_hi:[0,1]
	v_pk_add_f32 v[136:137], v[134:135], v[136:137] op_sel_hi:[0,1]
	v_pk_add_f32 v[134:135], v[134:135], v[154:155] op_sel_hi:[0,1]
	v_mfma_f32_32x32x16_bf16 v[118:133], v[76:79], v[0:3], v[118:133]
	s_mov_b64 s[2:3], 0
	v_mfma_f32_32x32x16_bf16 v[134:149], v[80:83], v[0:3], v[134:149]

; #define LAS __attribute__((address_space(3)))
; template <int MODE>
; __device__ __forceinline__ void attn_unit(LAS unsigned char* lds, const Ptrs& P, int nq, int nt_block, int qpos0, bool sample, int h,
;                                           const float* relb  , const float* lamp, const float* subg, bf16_t* Obase  , int wv) {
;     ...
;                     p0 = __builtin_amdgcn_mfma_f32_32x32x16_bf16(kf[2], qf[1], p0, 0, 0, 0);
;                     p1 = __builtin_amdgcn_mfma_f32_32x32x16_bf16(kf[3], qf[1], p1, 0, 0, 0);
; #pragma unroll
;                     for (int ks = 0; ks < 2; ++ks) { kg2[2 * ks] = *(const LAS bf16x8*)(kb + 4096 + ks * 2048); kg2[2 * ks + 1] = *(const LAS bf16x8*)(kb + 4096 + ks * 2048 + 512); }
;                     softmax_def(p0, p1, first, cbias, mr1, ng1, l1, o1a, o1b);
;                     pack_p(p0, p1, pa);
;                 }
;                 bf16x8 vf[8];
;                 {
;                     f32x16 s0, s1;
;                     if (farT) {
;                         s0 = __builtin_amdgcn_mfma_f32_32x32x16_bf16(kg2[0], qf[2], ng2, 0, 0, 0);
;                         s1 = __builtin_amdgcn_mfma_f32_32x32x16_bf16(kg2[1], qf[2], ng2, 0, 0, 0);
;                     } else {
;                         const float nb = ng2[0] - cbias;
; #pragma unroll
;                         for (int r = 0; r < 16; ++r) { const int idx = ib + (r & 3) + 8 * (r >> 2); s0[r] = bt[idx] + nb; s1[r] = bt[idx + 32] + nb; }
;                         s0 = __builtin_amdgcn_mfma_f32_32x32x16_bf16(kg2[0], qf[2], s0, 0, 0, 0);
;                         s1 = __builtin_amdgcn_mfma_f32_32x32x16_bf16(kg2[1], qf[2], s1, 0, 0, 0);
;                     }
;                     s0 = __builtin_amdgcn_mfma_f32_32x32x16_bf16(kg2[2], qf[3], s0, 0, 0, 0);
;                     s1 = __builtin_amdgcn_mfma_f32_32x32x16_bf16(kg2[3], qf[3], s1, 0, 0, 0);
.LBB0_1231:
	s_waitcnt lgkmcnt(1)
	v_mfma_f32_32x32x16_bf16 v[118:133], v[72:75], v[182:185], v[118:133]
	ds_read_b128 v[80:83], v4 offset:4096
	ds_read_b128 v[210:213], v4 offset:4608
	ds_read_b128 v[76:79], v4 offset:6144
	ds_read_b128 v[72:75], v4 offset:6656
	s_cmp_eq_u32 s28, 0
	s_cselect_b64 s[24:25], -1, 0
	s_cselect_b64 s[2:3], 0, -1
	s_and_b64 vcc, exec, s[2:3]
	s_waitcnt lgkmcnt(4)
	v_mfma_f32_32x32x16_bf16 v[134:149], v[150:153], v[182:185], v[134:149]
	s_cmp_lg_u64 s[26:27], 0
	s_cbranch_scc1 .Lqk2h_near_p
	s_waitcnt lgkmcnt(3)
	v_mfma_f32_32x32x16_bf16 v[166:181], v[80:83], v[186:189], v[86:101]
	s_waitcnt lgkmcnt(2)
	v_mfma_f32_32x32x16_bf16 v[150:165], v[210:213], v[186:189], v[86:101]
	s_waitcnt lgkmcnt(1)
	v_mfma_f32_32x32x16_bf16 v[166:181], v[76:79], v[190:193], v[166:181]
	s_waitcnt lgkmcnt(0)
	v_mfma_f32_32x32x16_bf16 v[150:165], v[72:75], v[190:193], v[150:165]
	v_max_f32_e32 v4, v118, v119
	s_nop 0

; template <int MODE>
; __device__ __forceinline__ void attn_unit(LAS unsigned char* lds, const Ptrs& P, int nq, int nt_block, int qpos0, bool sample, int h,
;                                           const float* relb  , const float* lamp, const float* subg, bf16_t* Obase  , int wv) {
;     ...
;                         const float nb = ng2[0] - cbias;
; #pragma unroll
;                         for (int r = 0; r < 16; ++r) { const int idx = ib + (r & 3) + 8 * (r >> 2); s0[r] = bt[idx] + nb; s1[r] = bt[idx + 32] + nb; }
;                         s0 = __builtin_amdgcn_mfma_f32_32x32x16_bf16(kg2[0], qf[2], s0, 0, 0, 0);
;                         s1 = __builtin_amdgcn_mfma_f32_32x32x16_bf16(kg2[1], qf[2], s1, 0, 0, 0);
.LBB0_1239:
	s_and_b64 vcc, exec, s[2:3]
	s_cmp_lg_u64 s[26:27], 0
	s_cbranch_scc0 .Lqk2h_done_p
	v_add_u32_e32 v164, 0x14000, v84
	v_sub_f32_e32 v4, v86, v70
	ds_read2_b32 v[84:85], v164 offset1:1
	ds_read2_b32 v[150:151], v164 offset0:2 offset1:3
	ds_read2_b32 v[152:153], v164 offset0:8 offset1:9
	ds_read2_b32 v[154:155], v164 offset0:10 offset1:11
	ds_read2_b32 v[156:157], v164 offset0:16 offset1:17
	ds_read2_b32 v[158:159], v164 offset0:18 offset1:19
	ds_read2_b32 v[160:161], v164 offset0:24 offset1:25
	ds_read2_b32 v[162:163], v164 offset0:26 offset1:27
	ds_read2_b32 v[236:237], v164 offset0:32 offset1:33
	ds_read2_b32 v[238:239], v164 offset0:34 offset1:35
	ds_read2_b32 v[240:241], v164 offset0:40 offset1:41
	ds_read2_b32 v[242:243], v164 offset0:42 offset1:43
	s_waitcnt lgkmcnt(4)
	v_pk_add_f32 v[180:181], v[4:5], v[162:163] op_sel_hi:[0,1]
	v_pk_add_f32 v[178:179], v[4:5], v[160:161] op_sel_hi:[0,1]
	v_pk_add_f32 v[176:177], v[4:5], v[158:159] op_sel_hi:[0,1]
	v_pk_add_f32 v[174:175], v[4:5], v[156:157] op_sel_hi:[0,1]
	ds_read2_b32 v[156:157], v164 offset0:48 offset1:49
	ds_read2_b32 v[158:159], v164 offset0:50 offset1:51
	ds_read2_b32 v[160:161], v164 offset0:56 offset1:57
	ds_read2_b32 v[162:163], v164 offset0:58 offset1:59
	v_pk_add_f32 v[172:173], v[4:5], v[154:155] op_sel_hi:[0,1]
	v_pk_add_f32 v[170:171], v[4:5], v[152:153] op_sel_hi:[0,1]
	v_pk_add_f32 v[168:169], v[4:5], v[150:151] op_sel_hi:[0,1]
	v_pk_add_f32 v[166:167], v[4:5], v[84:85] op_sel_hi:[0,1]
	s_waitcnt lgkmcnt(0)
	v_pk_add_f32 v[164:165], v[4:5], v[162:163] op_sel_hi:[0,1]
	v_pk_add_f32 v[162:163], v[4:5], v[160:161] op_sel_hi:[0,1]
	v_pk_add_f32 v[160:161], v[4:5], v[158:159] op_sel_hi:[0,1]
	v_pk_add_f32 v[158:159], v[4:5], v[156:157] op_sel_hi:[0,1]
	v_pk_add_f32 v[156:157], v[4:5], v[242:243] op_sel_hi:[0,1]
	v_pk_add_f32 v[154:155], v[4:5], v[240:241] op_sel_hi:[0,1]
	v_pk_add_f32 v[152:153], v[4:5], v[238:239] op_sel_hi:[0,1]
	v_pk_add_f32 v[150:151], v[4:5], v[236:237] op_sel_hi:[0,1]
	v_mfma_f32_32x32x16_bf16 v[166:181], v[80:83], v[186:189], v[166:181]
	s_nop 0
	v_mfma_f32_32x32x16_bf16 v[150:165], v[210:213], v[186:189], v[150:165]
	s_cbranch_execz .LBB0_1242
	s_branch .LBB0_1243
